# P10 attention K/V staging: all loads issued up-front, single wait (prompt+sample paths hand-written)
# speedup vs baseline: 1.0072x; 1.0072x over previous
.LBB0_1113:
	s_cmpk_gt_i32 s60, 0xff
	s_mov_b64 s[34:35], -1
	s_cbranch_scc0 .LBB0_1157
	s_add_i32 s34, s60, 0xffffff00
	s_and_b32 s35, s60, 3
	v_readfirstlane_b32 s36, v143
	s_and_b32 s67, s34, -4
	s_lshl_b32 s34, s34, 5
	s_lshr_b32 s61, s36, 6
	s_lshl_b32 s36, s35, 3
	v_add_u32_e32 v2, s67, v21
	v_mov_b32_e32 v3, v19
	s_and_b32 s76, s34, 0x7fffff80
	s_add_i32 s61, s61, s36
	v_lshlrev_b64 v[38:39], 12, v[2:3]
	v_or_b32_e32 v10, s76, v29
	v_mov_b32_e32 v11, v19
	v_readlane_b32 s80, v242, 31
	v_lshl_add_u64 v[2:3], s[50:51], 0, v[38:39]
	s_lshl_b32 s62, s61, 7
	v_lshlrev_b64 v[10:11], 10, v[10:11]
	v_readlane_b32 s86, v242, 37
	v_readlane_b32 s87, v242, 38
	v_lshl_add_u64 v[2:3], v[2:3], 0, s[62:63]
	s_lshl_b32 s62, s35, 8
	v_lshl_add_u64 v[10:11], s[86:87], 0, v[10:11]
	v_lshl_add_u64 v[10:11], v[10:11], 0, s[62:63]
	v_mov_b32_e32 v37, v19
	v_lshl_add_u64 v[2:3], v[2:3], 0, v[18:19]
	v_lshl_add_u64 v[14:15], v[10:11], 0, v[36:37]
	global_load_dwordx4 v[6:9], v[2:3], off
	s_nop 0
	global_load_dwordx4 v[2:5], v[2:3], off offset:64
	s_barrier
	v_readlane_b32 s86, v242, 37
	v_readlane_b32 s87, v242, 38
	v_readlane_b32 s88, v242, 39
	v_readlane_b32 s89, v242, 40
	v_lshrrev_b32_e32 v150, 3, v143
	v_and_b32_e32 v151, 7, v143
	v_and_b32_e32 v152, 0xff, v143
	v_lshrrev_b32_e32 v153, 8, v143
	v_mul_u32_u24_e32 v154, 0x90, v150
	v_lshl_add_u32 v154, v151, 4, v154
	v_mul_u32_u24_e32 v155, 0x1080, v153
	v_lshl_add_u32 v155, v152, 1, v155
	v_add_u32_e32 v148, 0x4200, v155
	s_lshl_b32 s62, s35, 8
	s_lshl_b32 s66, s35, 7
	s_add_i32 s67, s67, 0x2000
	v_add_u32_e32 v156, s76, v150
	v_lshlrev_b32_e32 v156, 10, v156
	v_lshl_add_u32 v157, v151, 5, s62
	v_add_u32_e32 v156, v156, v157
	v_add_u32_e32 v157, 0x10000, v156
	v_add_u32_e32 v158, s76, v152
	v_lshlrev_b32_e32 v158, 10, v158
	v_lshl_add_u32 v159, v153, 5, s62
	v_add_u32_e32 v158, v158, v159
	v_add_u32_e32 v149, s67, v150
	v_lshlrev_b32_e32 v149, 9, v149
	v_lshl_add_u32 v147, v151, 4, s66
	v_add_u32_e32 v149, v149, v147
	v_add_u32_e32 v146, 0xffffff80, v152
	v_add_u32_e32 v147, s67, v146
	v_lshlrev_b32_e32 v147, 9, v147
	v_lshl_add_u32 v145, v153, 4, s66
	v_add_u32_e32 v147, v147, v145
	v_mov_b32_e32 v176, 0
	v_mov_b32_e32 v177, 0
	v_mov_b32_e32 v178, 0
	v_mov_b32_e32 v179, 0
	v_mov_b32_e32 v180, 0
	v_mov_b32_e32 v181, 0
	v_mov_b32_e32 v182, 0
	v_mov_b32_e32 v183, 0
	v_mov_b32_e32 v188, 0
	v_mov_b32_e32 v189, 0
	v_mov_b32_e32 v190, 0
	v_mov_b32_e32 v191, 0
	v_mov_b32_e32 v196, 0
	v_mov_b32_e32 v197, 0
	v_mov_b32_e32 v198, 0
	v_mov_b32_e32 v199, 0
	v_mov_b32_e32 v204, 0
	v_mov_b32_e32 v205, 0
	v_mov_b32_e32 v206, 0
	v_mov_b32_e32 v207, 0
	global_load_dwordx4 v[160:163], v156, s[86:87]
	global_load_dwordx4 v[164:167], v156, s[86:87] offset:16
	global_load_dwordx4 v[168:171], v157, s[86:87]
	global_load_dwordx4 v[172:175], v157, s[86:87] offset:16
	v_cmp_gt_u32_e32 vcc, 0x80, v152
	s_and_saveexec_b64 s[36:37], vcc
	global_load_dwordx4 v[180:183], v158, s[88:89]
	global_load_dwordx4 v[184:187], v158, s[88:89] offset:16
	global_load_dwordx4 v[188:191], v158, s[88:89] offset:64
	global_load_dwordx4 v[192:195], v158, s[88:89] offset:80
	global_load_dwordx4 v[196:199], v158, s[88:89] offset:128
	global_load_dwordx4 v[200:203], v158, s[88:89] offset:144
	global_load_dwordx4 v[204:207], v158, s[88:89] offset:192
	global_load_dwordx4 v[208:211], v158, s[88:89] offset:208
	s_mov_b64 exec, s[36:37]
	v_cmp_gt_u32_e32 vcc, 32, v143
	s_and_saveexec_b64 s[36:37], vcc
	global_load_dwordx4 v[176:179], v149, s[48:49]
	s_mov_b64 exec, s[36:37]
	v_cmp_gt_u32_e32 vcc, 4, v146
	s_and_saveexec_b64 s[36:37], vcc
	global_load_dwordx4 v[180:183], v147, s[54:55]
	global_load_dwordx4 v[188:191], v147, s[54:55] offset:32
	global_load_dwordx4 v[196:199], v147, s[54:55] offset:64
	global_load_dwordx4 v[204:207], v147, s[54:55] offset:96
	s_mov_b64 exec, s[36:37]
	s_waitcnt vmcnt(0)
	v_cvt_pk_bf16_f32 v160, v160, v161
	v_cvt_pk_bf16_f32 v161, v162, v163
	v_cvt_pk_bf16_f32 v162, v164, v165
	v_cvt_pk_bf16_f32 v163, v166, v167
	v_cvt_pk_bf16_f32 v168, v168, v169
	v_cvt_pk_bf16_f32 v169, v170, v171
	v_cvt_pk_bf16_f32 v170, v172, v173
	v_cvt_pk_bf16_f32 v171, v174, v175
	ds_write_b128 v154, v[160:163]
	ds_write_b128 v154, v[168:171] offset:9216
	v_cmp_gt_u32_e32 vcc, 0x100, v143
	s_and_saveexec_b64 s[36:37], vcc
	ds_write_b128 v154, v[176:179] offset:18432
	s_mov_b64 exec, s[36:37]
	v_cmp_gt_u32_e32 vcc, 0x80, v152
	s_and_saveexec_b64 s[36:37], vcc
	v_cvt_pk_bf16_f32 v180, v180, v181
	v_cvt_pk_bf16_f32 v181, v182, v183
	v_cvt_pk_bf16_f32 v182, v184, v185
	v_cvt_pk_bf16_f32 v183, v186, v187
	v_cvt_pk_bf16_f32 v188, v188, v189
	v_cvt_pk_bf16_f32 v189, v190, v191
	v_cvt_pk_bf16_f32 v190, v192, v193
	v_cvt_pk_bf16_f32 v191, v194, v195
	v_cvt_pk_bf16_f32 v196, v196, v197
	v_cvt_pk_bf16_f32 v197, v198, v199
	v_cvt_pk_bf16_f32 v198, v200, v201
	v_cvt_pk_bf16_f32 v199, v202, v203
	v_cvt_pk_bf16_f32 v204, v204, v205
	v_cvt_pk_bf16_f32 v205, v206, v207
	v_cvt_pk_bf16_f32 v206, v208, v209
	v_cvt_pk_bf16_f32 v207, v210, v211
	s_mov_b64 exec, s[36:37]
	v_cmp_gt_u32_e32 vcc, 0xa0, v152
	s_and_saveexec_b64 s[36:37], vcc
	ds_write_b16 v155, v180 offset:36864
	ds_write_b16_d16_hi v155, v180 offset:37392
	ds_write_b16 v155, v181 offset:37920
	ds_write_b16_d16_hi v155, v181 offset:38448
	ds_write_b16 v155, v182 offset:38976
	ds_write_b16_d16_hi v155, v182 offset:39504
	ds_write_b16 v155, v183 offset:40032
	ds_write_b16_d16_hi v155, v183 offset:40560
	ds_write_b16 v155, v188 offset:45312
	ds_write_b16_d16_hi v155, v188 offset:45840
	ds_write_b16 v155, v189 offset:46368
	ds_write_b16_d16_hi v155, v189 offset:46896
	ds_write_b16 v155, v190 offset:47424
	ds_write_b16_d16_hi v155, v190 offset:47952
	ds_write_b16 v155, v191 offset:48480
	ds_write_b16_d16_hi v155, v191 offset:49008
	ds_write_b16 v148, v196 offset:36864
	ds_write_b16_d16_hi v148, v196 offset:37392
	ds_write_b16 v148, v197 offset:37920
	ds_write_b16_d16_hi v148, v197 offset:38448
	ds_write_b16 v148, v198 offset:38976
	ds_write_b16_d16_hi v148, v198 offset:39504
	ds_write_b16 v148, v199 offset:40032
	ds_write_b16_d16_hi v148, v199 offset:40560
	ds_write_b16 v148, v204 offset:45312
	ds_write_b16_d16_hi v148, v204 offset:45840
	ds_write_b16 v148, v205 offset:46368
	ds_write_b16_d16_hi v148, v205 offset:46896
	ds_write_b16 v148, v206 offset:47424
	ds_write_b16_d16_hi v148, v206 offset:47952
	ds_write_b16 v148, v207 offset:48480
	ds_write_b16_d16_hi v148, v207 offset:49008
	s_mov_b64 exec, s[36:37]
	s_mov_b64 s[34:35], exec

.LBB0_1157:
	s_and_b64 vcc, exec, s[34:35]
	s_cbranch_vccz .LBB0_1112
	s_bfe_u32 s34, s60, 0x20004
	v_readfirstlane_b32 s35, v143
	s_lshr_b32 s67, s35, 6
	s_lshl_b32 s35, s34, 3
	s_and_b32 s61, s60, 15
	s_add_i32 s67, s67, s35
	s_lshl_b32 s35, s60, 5
	s_and_b32 s35, s35, 0xfffff800
	s_lshl_b32 s36, s61, 7
	s_or_b32 s66, s36, s35
	v_or_b32_e32 v2, s66, v1
	v_ashrrev_i32_e32 v3, 31, v2
	v_lshlrev_b64 v[2:3], 12, v[2:3]
	v_lshl_add_u64 v[2:3], s[50:51], 0, v[2:3]
	s_lshl_b32 s62, s67, 7
	v_lshl_add_u64 v[2:3], v[2:3], 0, s[62:63]
	v_lshl_add_u64 v[2:3], v[2:3], 0, v[18:19]
	global_load_dwordx4 v[14:17], v[2:3], off
	global_load_dwordx4 v[10:13], v[2:3], off offset:64
	s_lshl_b32 s76, s34, 6
	s_cmp_lg_u32 s61, 0
	s_cselect_b64 s[78:79], -1, 0
	s_addk_i32 s66, 0xff80
	s_cmp_eq_u32 s61, 0
	v_lshlrev_b32_e32 v38, 1, v20
	s_waitcnt lgkmcnt(0)
	s_barrier
	v_lshrrev_b32_e32 v150, 3, v143
	v_and_b32_e32 v151, 7, v143
	v_and_b32_e32 v152, 0xff, v143
	v_lshrrev_b32_e32 v153, 8, v143
	v_mul_u32_u24_e32 v154, 0x90, v150
	v_lshl_add_u32 v154, v151, 4, v154
	v_mul_u32_u24_e32 v155, 0x1080, v153
	v_lshl_add_u32 v155, v152, 1, v155
	v_add_u32_e32 v148, 0x4200, v155
	s_lshl_b32 s62, s76, 1
	v_add_u32_e32 v156, s66, v150
	v_lshlrev_b32_e32 v156, 9, v156
	v_lshl_add_u32 v157, v151, 4, s62
	v_add_u32_e32 v156, v156, v157
	v_add_u32_e32 v157, 0x8000, v156
	v_add_u32_e32 v159, 0x10000, v156
	v_add_u32_e32 v149, 0x18000, v156
	v_add_u32_e32 v158, s66, v152
	v_lshlrev_b32_e32 v158, 9, v158
	v_lshl_add_u32 v147, v153, 4, s62
	v_add_u32_e32 v158, v158, v147
	s_cmp_eq_u32 s61, 0
	s_cbranch_scc1 .Lat_pfirst
	global_load_dwordx4 v[160:163], v156, s[48:49]
	global_load_dwordx4 v[164:167], v157, s[48:49]
	global_load_dwordx4 v[168:171], v159, s[48:49]
	global_load_dwordx4 v[172:175], v149, s[48:49]
	global_load_dwordx4 v[176:179], v158, s[54:55]
	global_load_dwordx4 v[180:183], v158, s[54:55] offset:32
	global_load_dwordx4 v[184:187], v158, s[54:55] offset:64
	global_load_dwordx4 v[188:191], v158, s[54:55] offset:96
	s_branch .Lat_pwait
.Lat_pfirst:
	v_mov_b32_e32 v160, 0
	v_mov_b32_e32 v161, 0
	v_mov_b32_e32 v162, 0
	v_mov_b32_e32 v163, 0
	v_mov_b32_e32 v164, 0
	v_mov_b32_e32 v165, 0
	v_mov_b32_e32 v166, 0
	v_mov_b32_e32 v167, 0
	v_mov_b32_e32 v176, 0
	v_mov_b32_e32 v177, 0
	v_mov_b32_e32 v178, 0
	v_mov_b32_e32 v179, 0
	v_mov_b32_e32 v180, 0
	v_mov_b32_e32 v181, 0
	v_mov_b32_e32 v182, 0
	v_mov_b32_e32 v183, 0
	v_mov_b32_e32 v184, 0
	v_mov_b32_e32 v185, 0
	v_mov_b32_e32 v186, 0
	v_mov_b32_e32 v187, 0
	v_mov_b32_e32 v188, 0
	v_mov_b32_e32 v189, 0
	v_mov_b32_e32 v190, 0
	v_mov_b32_e32 v191, 0
	global_load_dwordx4 v[168:171], v159, s[48:49]
	global_load_dwordx4 v[172:175], v149, s[48:49]
	v_cmp_lt_u32_e32 vcc, 0x7f, v152
	s_and_saveexec_b64 s[36:37], vcc
	global_load_dwordx4 v[176:179], v158, s[54:55]
	global_load_dwordx4 v[180:183], v158, s[54:55] offset:32
	global_load_dwordx4 v[184:187], v158, s[54:55] offset:64
	global_load_dwordx4 v[188:191], v158, s[54:55] offset:96
	s_mov_b64 exec, s[36:37]
.Lat_pwait:
	s_waitcnt vmcnt(0)
	ds_write_b128 v154, v[160:163]
	ds_write_b128 v154, v[164:167] offset:9216
	ds_write_b128 v154, v[168:171] offset:18432
	ds_write_b128 v154, v[172:175] offset:27648
	ds_write_b16 v155, v176 offset:36864
	ds_write_b16_d16_hi v155, v176 offset:37392
	ds_write_b16 v155, v177 offset:37920
	ds_write_b16_d16_hi v155, v177 offset:38448
	ds_write_b16 v155, v178 offset:38976
	ds_write_b16_d16_hi v155, v178 offset:39504
	ds_write_b16 v155, v179 offset:40032
	ds_write_b16_d16_hi v155, v179 offset:40560
	ds_write_b16 v155, v180 offset:45312
	ds_write_b16_d16_hi v155, v180 offset:45840
	ds_write_b16 v155, v181 offset:46368
	ds_write_b16_d16_hi v155, v181 offset:46896
	ds_write_b16 v155, v182 offset:47424
	ds_write_b16_d16_hi v155, v182 offset:47952
	ds_write_b16 v155, v183 offset:48480
	ds_write_b16_d16_hi v155, v183 offset:49008
	ds_write_b16 v148, v184 offset:36864
	ds_write_b16_d16_hi v148, v184 offset:37392
	ds_write_b16 v148, v185 offset:37920
	ds_write_b16_d16_hi v148, v185 offset:38448
	ds_write_b16 v148, v186 offset:38976
	ds_write_b16_d16_hi v148, v186 offset:39504
	ds_write_b16 v148, v187 offset:40032
	ds_write_b16_d16_hi v148, v187 offset:40560
	ds_write_b16 v148, v188 offset:45312
	ds_write_b16_d16_hi v148, v188 offset:45840
	ds_write_b16 v148, v189 offset:46368
	ds_write_b16_d16_hi v148, v189 offset:46896
	ds_write_b16 v148, v190 offset:47424
	ds_write_b16_d16_hi v148, v190 offset:47952
	ds_write_b16 v148, v191 offset:48480
	ds_write_b16_d16_hi v148, v191 offset:49008
	s_mov_b32 s66, 0
	s_lshl_b32 s34, s67, 2
	v_readlane_b32 s80, v242, 0
	v_mov_b32_e32 v2, s34
	v_readlane_b32 s81, v242, 1
	s_waitcnt lgkmcnt(0)
	s_barrier
	v_and_b32_e32 v3, 64, v53
	v_add_u32_e32 v3, 64, v3
	s_nop 0
	global_load_dword v37, v2, s[80:81]
	v_xor_b32_e32 v2, 16, v53
	v_cmp_lt_i32_e32 vcc, v2, v3
	s_and_b32 s36, s59, 15
	s_lshl_b32 s34, s67, 6
	v_cndmask_b32_e32 v2, v53, v2, vcc
	v_lshlrev_b32_e32 v55, 2, v2
	v_xor_b32_e32 v2, 32, v53
	v_cmp_lt_i32_e32 vcc, v2, v3
	s_and_b32 s35, s42, 0xfffff800
	s_lshl_b32 s36, s36, 7
	v_cndmask_b32_e32 v2, v53, v2, vcc
	s_or_b32 s35, s35, s36
	v_lshlrev_b32_e32 v56, 2, v2
	s_lshl_b32 s62, s34, 1
	v_mov_b64_e32 v[2:3], v[10:11]
	v_mov_b64_e32 v[6:7], v[14:15]
	v_lshl_add_u64 v[38:39], v[34:35], 0, s[62:63]
	v_or_b32_e32 v57, s35, v1
	s_mov_b32 s34, 0
	v_mov_b64_e32 v[4:5], v[12:13]
	v_mov_b64_e32 v[8:9], v[16:17]
	v_readlane_b32 s82, v242, 2
	v_readlane_b32 s83, v242, 3
	v_readlane_b32 s84, v242, 4
	v_readlane_b32 s85, v242, 5
	v_readlane_b32 s86, v242, 6
	v_readlane_b32 s87, v242, 7
	s_branch .LBB0_1177
